# P6 EpiPleNorm part 1 rewritten: ple/x1b loads 4 row-groups deep ahead of the sigmoid-fma math
# speedup vs baseline: 1.0024x; 1.0024x over previous
.LBB0_1134:
	v_lshrrev_b32_e32 v128, 2, v142
	s_lshl_b32 s24, s18, 8
	v_and_b32_e32 v128, 12, v128
	s_add_i32 s5, s24, s59
	s_lshl_b32 s4, s20, 8
	v_lshl_or_b32 v128, s19, 5, v128
	v_or_b32_e32 v130, s5, v143
	v_or_b32_e32 v128, s4, v128
	v_ashrrev_i32_e32 v131, 31, v130
	v_ashrrev_i32_e32 v129, 31, v128
	v_lshlrev_b64 v[132:133], 10, v[130:131]
	v_lshl_add_u64 v[132:133], v[132:133], 0, v[128:129]
	v_lshlrev_b64 v[132:133], 1, v[132:133]
	s_ashr_i32 s5, s4, 31
	v_lshl_add_u64 v[134:135], s[8:9], 0, v[132:133]
	v_lshlrev_b64 v[136:137], 11, v[130:131]
	v_lshl_add_u64 v[138:139], s[16:17], 0, v[132:133]
	v_or_b32_e32 v140, 32, v132
	v_mov_b32_e32 v141, v133
	v_lshl_add_u64 v[134:135], v[134:135], 0, v[136:137]
	s_lshl_b64 s[4:5], s[4:5], 1
	v_or_b32_e32 v150, 0x100, v132
	v_mov_b32_e32 v151, v133
	s_barrier
	v_lshl_add_u64 v[134:135], v[134:135], 0, s[4:5]
	s_mov_b64 s[94:95], 0x8000
	s_mov_b64 s[96:97], 0x10000
	s_mov_b64 s[98:99], 0x28000
	s_mov_b64 s[100:101], 0x50000
	global_load_dwordx2 v[160:161], v[134:135], off nt
	global_load_dwordx2 v[162:163], v[134:135], off offset:32 nt
	global_load_dwordx2 v[164:165], v[134:135], off offset:256 nt
	global_load_dwordx2 v[166:167], v[134:135], off offset:288 nt
	global_load_dwordx2 v[168:169], v[138:139], off
	global_load_dwordx2 v[170:171], v[138:139], off offset:32
	global_load_dwordx2 v[172:173], v[138:139], off offset:256
	global_load_dwordx2 v[174:175], v[138:139], off offset:288
	v_lshl_add_u64 v[134:135], v[134:135], 0, s[96:97]
	v_lshl_add_u64 v[138:139], v[138:139], 0, s[94:95]
	global_load_dwordx2 v[176:177], v[134:135], off nt
	global_load_dwordx2 v[178:179], v[134:135], off offset:32 nt
	global_load_dwordx2 v[180:181], v[134:135], off offset:256 nt
	global_load_dwordx2 v[182:183], v[134:135], off offset:288 nt
	global_load_dwordx2 v[184:185], v[138:139], off
	global_load_dwordx2 v[186:187], v[138:139], off offset:32
	global_load_dwordx2 v[188:189], v[138:139], off offset:256
	global_load_dwordx2 v[190:191], v[138:139], off offset:288
	v_lshl_add_u64 v[134:135], v[134:135], 0, s[96:97]
	v_lshl_add_u64 v[138:139], v[138:139], 0, s[94:95]
	global_load_dwordx2 v[192:193], v[134:135], off nt
	global_load_dwordx2 v[194:195], v[134:135], off offset:32 nt
	global_load_dwordx2 v[196:197], v[134:135], off offset:256 nt
	global_load_dwordx2 v[198:199], v[134:135], off offset:288 nt
	global_load_dwordx2 v[200:201], v[138:139], off
	global_load_dwordx2 v[202:203], v[138:139], off offset:32
	global_load_dwordx2 v[204:205], v[138:139], off offset:256
	global_load_dwordx2 v[206:207], v[138:139], off offset:288
	v_lshl_add_u64 v[134:135], v[134:135], 0, s[96:97]
	v_lshl_add_u64 v[138:139], v[138:139], 0, s[94:95]
	global_load_dwordx2 v[208:209], v[134:135], off nt
	global_load_dwordx2 v[210:211], v[134:135], off offset:32 nt
	global_load_dwordx2 v[212:213], v[134:135], off offset:256 nt
	global_load_dwordx2 v[214:215], v[134:135], off offset:288 nt
	global_load_dwordx2 v[216:217], v[138:139], off
	global_load_dwordx2 v[218:219], v[138:139], off offset:32
	global_load_dwordx2 v[220:221], v[138:139], off offset:256
	global_load_dwordx2 v[222:223], v[138:139], off offset:288
	v_lshl_add_u64 v[134:135], v[134:135], 0, s[100:101]
	v_lshl_add_u64 v[138:139], v[138:139], 0, s[98:99]
	v_mul_f32_e32 v68, 0xbfb8aa3b, v68
	v_mul_f32_e32 v69, 0xbfb8aa3b, v69
	v_mul_f32_e32 v70, 0xbfb8aa3b, v70
	v_mul_f32_e32 v71, 0xbfb8aa3b, v71
	v_mul_f32_e32 v64, 0xbfb8aa3b, v64
	v_mul_f32_e32 v65, 0xbfb8aa3b, v65
	v_mul_f32_e32 v66, 0xbfb8aa3b, v66
	v_mul_f32_e32 v67, 0xbfb8aa3b, v67
	v_mul_f32_e32 v72, 0xbfb8aa3b, v72
	v_mul_f32_e32 v73, 0xbfb8aa3b, v73
	v_mul_f32_e32 v74, 0xbfb8aa3b, v74
	v_mul_f32_e32 v75, 0xbfb8aa3b, v75
	v_mul_f32_e32 v76, 0xbfb8aa3b, v76
	v_mul_f32_e32 v77, 0xbfb8aa3b, v77
	v_mul_f32_e32 v78, 0xbfb8aa3b, v78
	v_mul_f32_e32 v79, 0xbfb8aa3b, v79
	v_exp_f32_e32 v68, v68
	v_exp_f32_e32 v69, v69
	v_exp_f32_e32 v70, v70
	v_exp_f32_e32 v71, v71
	v_exp_f32_e32 v64, v64
	v_exp_f32_e32 v65, v65
	v_exp_f32_e32 v66, v66
	v_exp_f32_e32 v67, v67
	v_exp_f32_e32 v72, v72
	v_exp_f32_e32 v73, v73
	v_exp_f32_e32 v74, v74
	v_exp_f32_e32 v75, v75
	v_exp_f32_e32 v76, v76
	v_exp_f32_e32 v77, v77
	v_exp_f32_e32 v78, v78
	v_exp_f32_e32 v79, v79
	v_add_f32_e32 v68, 1.0, v68
	v_add_f32_e32 v69, 1.0, v69
	v_add_f32_e32 v70, 1.0, v70
	v_add_f32_e32 v71, 1.0, v71
	v_add_f32_e32 v64, 1.0, v64
	v_add_f32_e32 v65, 1.0, v65
	v_add_f32_e32 v66, 1.0, v66
	v_add_f32_e32 v67, 1.0, v67
	v_add_f32_e32 v72, 1.0, v72
	v_add_f32_e32 v73, 1.0, v73
	v_add_f32_e32 v74, 1.0, v74
	v_add_f32_e32 v75, 1.0, v75
	v_add_f32_e32 v76, 1.0, v76
	v_add_f32_e32 v77, 1.0, v77
	v_add_f32_e32 v78, 1.0, v78
	v_add_f32_e32 v79, 1.0, v79
	v_rcp_f32_e32 v240, v68
	v_rcp_f32_e32 v241, v69
	v_rcp_f32_e32 v242, v70
	v_rcp_f32_e32 v243, v71
	v_rcp_f32_e32 v244, v64
	v_rcp_f32_e32 v245, v65
	v_rcp_f32_e32 v246, v66
	v_rcp_f32_e32 v247, v67
	v_rcp_f32_e32 v248, v72
	v_rcp_f32_e32 v249, v73
	v_rcp_f32_e32 v250, v74
	v_rcp_f32_e32 v251, v75
	v_rcp_f32_e32 v252, v76
	v_rcp_f32_e32 v253, v77
	v_rcp_f32_e32 v254, v78
	v_rcp_f32_e32 v255, v79
	s_waitcnt vmcnt(24)
	v_lshlrev_b32_e32 v224, 16, v160
	v_and_b32_e32 v225, 0xffff0000, v160
	v_lshlrev_b32_e32 v226, 16, v161
	v_and_b32_e32 v227, 0xffff0000, v161
	v_lshlrev_b32_e32 v228, 16, v168
	v_and_b32_e32 v229, 0xffff0000, v168
	v_lshlrev_b32_e32 v230, 16, v169
	v_and_b32_e32 v231, 0xffff0000, v169
	v_pk_fma_f32 v[64:65], v[240:241], v[224:225], v[228:229]
	v_pk_fma_f32 v[66:67], v[242:243], v[226:227], v[230:231]
	v_lshlrev_b32_e32 v232, 16, v162
	v_and_b32_e32 v233, 0xffff0000, v162
	v_lshlrev_b32_e32 v234, 16, v163
	v_and_b32_e32 v235, 0xffff0000, v163
	v_lshlrev_b32_e32 v236, 16, v170
	v_and_b32_e32 v237, 0xffff0000, v170
	v_lshlrev_b32_e32 v238, 16, v171
	v_and_b32_e32 v239, 0xffff0000, v171
	v_pk_fma_f32 v[68:69], v[244:245], v[232:233], v[236:237]
	v_pk_fma_f32 v[70:71], v[246:247], v[234:235], v[238:239]
	v_lshlrev_b32_e32 v224, 16, v164
	v_and_b32_e32 v225, 0xffff0000, v164
	v_lshlrev_b32_e32 v226, 16, v165
	v_and_b32_e32 v227, 0xffff0000, v165
	v_lshlrev_b32_e32 v228, 16, v172
	v_and_b32_e32 v229, 0xffff0000, v172
	v_lshlrev_b32_e32 v230, 16, v173
	v_and_b32_e32 v231, 0xffff0000, v173
	v_pk_fma_f32 v[72:73], v[248:249], v[224:225], v[228:229]
	v_pk_fma_f32 v[74:75], v[250:251], v[226:227], v[230:231]
	v_lshlrev_b32_e32 v232, 16, v166
	v_and_b32_e32 v233, 0xffff0000, v166
	v_lshlrev_b32_e32 v234, 16, v167
	v_and_b32_e32 v235, 0xffff0000, v167
	v_lshlrev_b32_e32 v236, 16, v174
	v_and_b32_e32 v237, 0xffff0000, v174
	v_lshlrev_b32_e32 v238, 16, v175
	v_and_b32_e32 v239, 0xffff0000, v175
	v_pk_fma_f32 v[76:77], v[252:253], v[232:233], v[236:237]
	v_pk_fma_f32 v[78:79], v[254:255], v[234:235], v[238:239]
	global_load_dwordx2 v[160:161], v[134:135], off nt
	global_load_dwordx2 v[162:163], v[134:135], off offset:32 nt
	global_load_dwordx2 v[164:165], v[134:135], off offset:256 nt
	global_load_dwordx2 v[166:167], v[134:135], off offset:288 nt
	global_load_dwordx2 v[168:169], v[138:139], off
	global_load_dwordx2 v[170:171], v[138:139], off offset:32
	global_load_dwordx2 v[172:173], v[138:139], off offset:256
	global_load_dwordx2 v[174:175], v[138:139], off offset:288
	v_lshl_add_u64 v[134:135], v[134:135], 0, s[96:97]
	v_lshl_add_u64 v[138:139], v[138:139], 0, s[94:95]
	v_mul_f32_e32 v88, 0xbfb8aa3b, v88
	v_mul_f32_e32 v89, 0xbfb8aa3b, v89
	v_mul_f32_e32 v90, 0xbfb8aa3b, v90
	v_mul_f32_e32 v91, 0xbfb8aa3b, v91
	v_mul_f32_e32 v96, 0xbfb8aa3b, v96
	v_mul_f32_e32 v97, 0xbfb8aa3b, v97
	v_mul_f32_e32 v98, 0xbfb8aa3b, v98
	v_mul_f32_e32 v99, 0xbfb8aa3b, v99
	v_mul_f32_e32 v100, 0xbfb8aa3b, v100
	v_mul_f32_e32 v101, 0xbfb8aa3b, v101
	v_mul_f32_e32 v102, 0xbfb8aa3b, v102
	v_mul_f32_e32 v103, 0xbfb8aa3b, v103
	v_mul_f32_e32 v108, 0xbfb8aa3b, v108
	v_mul_f32_e32 v109, 0xbfb8aa3b, v109
	v_mul_f32_e32 v110, 0xbfb8aa3b, v110
	v_mul_f32_e32 v111, 0xbfb8aa3b, v111
	v_exp_f32_e32 v88, v88
	v_exp_f32_e32 v89, v89
	v_exp_f32_e32 v90, v90
	v_exp_f32_e32 v91, v91
	v_exp_f32_e32 v96, v96
	v_exp_f32_e32 v97, v97
	v_exp_f32_e32 v98, v98
	v_exp_f32_e32 v99, v99
	v_exp_f32_e32 v100, v100
	v_exp_f32_e32 v101, v101
	v_exp_f32_e32 v102, v102
	v_exp_f32_e32 v103, v103
	v_exp_f32_e32 v108, v108
	v_exp_f32_e32 v109, v109
	v_exp_f32_e32 v110, v110
	v_exp_f32_e32 v111, v111
	v_add_f32_e32 v88, 1.0, v88
	v_add_f32_e32 v89, 1.0, v89
	v_add_f32_e32 v90, 1.0, v90
	v_add_f32_e32 v91, 1.0, v91
	v_add_f32_e32 v96, 1.0, v96
	v_add_f32_e32 v97, 1.0, v97
	v_add_f32_e32 v98, 1.0, v98
	v_add_f32_e32 v99, 1.0, v99
	v_add_f32_e32 v100, 1.0, v100
	v_add_f32_e32 v101, 1.0, v101
	v_add_f32_e32 v102, 1.0, v102
	v_add_f32_e32 v103, 1.0, v103
	v_add_f32_e32 v108, 1.0, v108
	v_add_f32_e32 v109, 1.0, v109
	v_add_f32_e32 v110, 1.0, v110
	v_add_f32_e32 v111, 1.0, v111
	v_rcp_f32_e32 v240, v88
	v_rcp_f32_e32 v241, v89
	v_rcp_f32_e32 v242, v90
	v_rcp_f32_e32 v243, v91
	v_rcp_f32_e32 v244, v96
	v_rcp_f32_e32 v245, v97
	v_rcp_f32_e32 v246, v98
	v_rcp_f32_e32 v247, v99
	v_rcp_f32_e32 v248, v100
	v_rcp_f32_e32 v249, v101
	v_rcp_f32_e32 v250, v102
	v_rcp_f32_e32 v251, v103
	v_rcp_f32_e32 v252, v108
	v_rcp_f32_e32 v253, v109
	v_rcp_f32_e32 v254, v110
	v_rcp_f32_e32 v255, v111
	s_waitcnt vmcnt(24)
	v_lshlrev_b32_e32 v224, 16, v176
	v_and_b32_e32 v225, 0xffff0000, v176
	v_lshlrev_b32_e32 v226, 16, v177
	v_and_b32_e32 v227, 0xffff0000, v177
	v_lshlrev_b32_e32 v228, 16, v184
	v_and_b32_e32 v229, 0xffff0000, v184
	v_lshlrev_b32_e32 v230, 16, v185
	v_and_b32_e32 v231, 0xffff0000, v185
	v_pk_fma_f32 v[88:89], v[240:241], v[224:225], v[228:229]
	v_pk_fma_f32 v[90:91], v[242:243], v[226:227], v[230:231]
	v_lshlrev_b32_e32 v232, 16, v178
	v_and_b32_e32 v233, 0xffff0000, v178
	v_lshlrev_b32_e32 v234, 16, v179
	v_and_b32_e32 v235, 0xffff0000, v179
	v_lshlrev_b32_e32 v236, 16, v186
	v_and_b32_e32 v237, 0xffff0000, v186
	v_lshlrev_b32_e32 v238, 16, v187
	v_and_b32_e32 v239, 0xffff0000, v187
	v_pk_fma_f32 v[96:97], v[244:245], v[232:233], v[236:237]
	v_pk_fma_f32 v[98:99], v[246:247], v[234:235], v[238:239]
	v_lshlrev_b32_e32 v224, 16, v180
	v_and_b32_e32 v225, 0xffff0000, v180
	v_lshlrev_b32_e32 v226, 16, v181
	v_and_b32_e32 v227, 0xffff0000, v181
	v_lshlrev_b32_e32 v228, 16, v188
	v_and_b32_e32 v229, 0xffff0000, v188
	v_lshlrev_b32_e32 v230, 16, v189
	v_and_b32_e32 v231, 0xffff0000, v189
	v_pk_fma_f32 v[100:101], v[248:249], v[224:225], v[228:229]
	v_pk_fma_f32 v[102:103], v[250:251], v[226:227], v[230:231]
	v_lshlrev_b32_e32 v232, 16, v182
	v_and_b32_e32 v233, 0xffff0000, v182
	v_lshlrev_b32_e32 v234, 16, v183
	v_and_b32_e32 v235, 0xffff0000, v183
	v_lshlrev_b32_e32 v236, 16, v190
	v_and_b32_e32 v237, 0xffff0000, v190
	v_lshlrev_b32_e32 v238, 16, v191
	v_and_b32_e32 v239, 0xffff0000, v191
	v_pk_fma_f32 v[108:109], v[252:253], v[232:233], v[236:237]
	v_pk_fma_f32 v[110:111], v[254:255], v[234:235], v[238:239]
	global_load_dwordx2 v[176:177], v[134:135], off nt
	global_load_dwordx2 v[178:179], v[134:135], off offset:32 nt
	global_load_dwordx2 v[180:181], v[134:135], off offset:256 nt
	global_load_dwordx2 v[182:183], v[134:135], off offset:288 nt
	global_load_dwordx2 v[184:185], v[138:139], off
	global_load_dwordx2 v[186:187], v[138:139], off offset:32
	global_load_dwordx2 v[188:189], v[138:139], off offset:256
	global_load_dwordx2 v[190:191], v[138:139], off offset:288
	v_lshl_add_u64 v[134:135], v[134:135], 0, s[96:97]
	v_lshl_add_u64 v[138:139], v[138:139], 0, s[94:95]
	v_mul_f32_e32 v120, 0xbfb8aa3b, v120
	v_mul_f32_e32 v121, 0xbfb8aa3b, v121
	v_mul_f32_e32 v122, 0xbfb8aa3b, v122
	v_mul_f32_e32 v123, 0xbfb8aa3b, v123
	v_mul_f32_e32 v124, 0xbfb8aa3b, v124
	v_mul_f32_e32 v125, 0xbfb8aa3b, v125
	v_mul_f32_e32 v126, 0xbfb8aa3b, v126
	v_mul_f32_e32 v127, 0xbfb8aa3b, v127
	v_mul_f32_e32 v116, 0xbfb8aa3b, v116
	v_mul_f32_e32 v117, 0xbfb8aa3b, v117
	v_mul_f32_e32 v118, 0xbfb8aa3b, v118
	v_mul_f32_e32 v119, 0xbfb8aa3b, v119
	v_mul_f32_e32 v112, 0xbfb8aa3b, v112
	v_mul_f32_e32 v113, 0xbfb8aa3b, v113
	v_mul_f32_e32 v114, 0xbfb8aa3b, v114
	v_mul_f32_e32 v115, 0xbfb8aa3b, v115
	v_exp_f32_e32 v120, v120
	v_exp_f32_e32 v121, v121
	v_exp_f32_e32 v122, v122
	v_exp_f32_e32 v123, v123
	v_exp_f32_e32 v124, v124
	v_exp_f32_e32 v125, v125
	v_exp_f32_e32 v126, v126
	v_exp_f32_e32 v127, v127
	v_exp_f32_e32 v116, v116
	v_exp_f32_e32 v117, v117
	v_exp_f32_e32 v118, v118
	v_exp_f32_e32 v119, v119
	v_exp_f32_e32 v112, v112
	v_exp_f32_e32 v113, v113
	v_exp_f32_e32 v114, v114
	v_exp_f32_e32 v115, v115
	v_add_f32_e32 v120, 1.0, v120
	v_add_f32_e32 v121, 1.0, v121
	v_add_f32_e32 v122, 1.0, v122
	v_add_f32_e32 v123, 1.0, v123
	v_add_f32_e32 v124, 1.0, v124
	v_add_f32_e32 v125, 1.0, v125
	v_add_f32_e32 v126, 1.0, v126
	v_add_f32_e32 v127, 1.0, v127
	v_add_f32_e32 v116, 1.0, v116
	v_add_f32_e32 v117, 1.0, v117
	v_add_f32_e32 v118, 1.0, v118
	v_add_f32_e32 v119, 1.0, v119
	v_add_f32_e32 v112, 1.0, v112
	v_add_f32_e32 v113, 1.0, v113
	v_add_f32_e32 v114, 1.0, v114
	v_add_f32_e32 v115, 1.0, v115
	v_rcp_f32_e32 v240, v120
	v_rcp_f32_e32 v241, v121
	v_rcp_f32_e32 v242, v122
	v_rcp_f32_e32 v243, v123
	v_rcp_f32_e32 v244, v124
	v_rcp_f32_e32 v245, v125
	v_rcp_f32_e32 v246, v126
	v_rcp_f32_e32 v247, v127
	v_rcp_f32_e32 v248, v116
	v_rcp_f32_e32 v249, v117
	v_rcp_f32_e32 v250, v118
	v_rcp_f32_e32 v251, v119
	v_rcp_f32_e32 v252, v112
	v_rcp_f32_e32 v253, v113
	v_rcp_f32_e32 v254, v114
	v_rcp_f32_e32 v255, v115
	s_waitcnt vmcnt(24)
	v_lshlrev_b32_e32 v224, 16, v192
	v_and_b32_e32 v225, 0xffff0000, v192
	v_lshlrev_b32_e32 v226, 16, v193
	v_and_b32_e32 v227, 0xffff0000, v193
	v_lshlrev_b32_e32 v228, 16, v200
	v_and_b32_e32 v229, 0xffff0000, v200
	v_lshlrev_b32_e32 v230, 16, v201
	v_and_b32_e32 v231, 0xffff0000, v201
	v_pk_fma_f32 v[120:121], v[240:241], v[224:225], v[228:229]
	v_pk_fma_f32 v[122:123], v[242:243], v[226:227], v[230:231]
	v_lshlrev_b32_e32 v232, 16, v194
	v_and_b32_e32 v233, 0xffff0000, v194
	v_lshlrev_b32_e32 v234, 16, v195
	v_and_b32_e32 v235, 0xffff0000, v195
	v_lshlrev_b32_e32 v236, 16, v202
	v_and_b32_e32 v237, 0xffff0000, v202
	v_lshlrev_b32_e32 v238, 16, v203
	v_and_b32_e32 v239, 0xffff0000, v203
	v_pk_fma_f32 v[124:125], v[244:245], v[232:233], v[236:237]
	v_pk_fma_f32 v[126:127], v[246:247], v[234:235], v[238:239]
	v_lshlrev_b32_e32 v224, 16, v196
	v_and_b32_e32 v225, 0xffff0000, v196
	v_lshlrev_b32_e32 v226, 16, v197
	v_and_b32_e32 v227, 0xffff0000, v197
	v_lshlrev_b32_e32 v228, 16, v204
	v_and_b32_e32 v229, 0xffff0000, v204
	v_lshlrev_b32_e32 v230, 16, v205
	v_and_b32_e32 v231, 0xffff0000, v205
	v_pk_fma_f32 v[116:117], v[248:249], v[224:225], v[228:229]
	v_pk_fma_f32 v[118:119], v[250:251], v[226:227], v[230:231]
	v_lshlrev_b32_e32 v232, 16, v198
	v_and_b32_e32 v233, 0xffff0000, v198
	v_lshlrev_b32_e32 v234, 16, v199
	v_and_b32_e32 v235, 0xffff0000, v199
	v_lshlrev_b32_e32 v236, 16, v206
	v_and_b32_e32 v237, 0xffff0000, v206
	v_lshlrev_b32_e32 v238, 16, v207
	v_and_b32_e32 v239, 0xffff0000, v207
	v_pk_fma_f32 v[112:113], v[252:253], v[232:233], v[236:237]
	v_pk_fma_f32 v[114:115], v[254:255], v[234:235], v[238:239]
	global_load_dwordx2 v[192:193], v[134:135], off nt
	global_load_dwordx2 v[194:195], v[134:135], off offset:32 nt
	global_load_dwordx2 v[196:197], v[134:135], off offset:256 nt
	global_load_dwordx2 v[198:199], v[134:135], off offset:288 nt
	global_load_dwordx2 v[200:201], v[138:139], off
	global_load_dwordx2 v[202:203], v[138:139], off offset:32
	global_load_dwordx2 v[204:205], v[138:139], off offset:256
	global_load_dwordx2 v[206:207], v[138:139], off offset:288
	v_lshl_add_u64 v[134:135], v[134:135], 0, s[96:97]
	v_lshl_add_u64 v[138:139], v[138:139], 0, s[94:95]
	v_mul_f32_e32 v104, 0xbfb8aa3b, v104
	v_mul_f32_e32 v105, 0xbfb8aa3b, v105
	v_mul_f32_e32 v106, 0xbfb8aa3b, v106
	v_mul_f32_e32 v107, 0xbfb8aa3b, v107
	v_mul_f32_e32 v92, 0xbfb8aa3b, v92
	v_mul_f32_e32 v93, 0xbfb8aa3b, v93
	v_mul_f32_e32 v94, 0xbfb8aa3b, v94
	v_mul_f32_e32 v95, 0xbfb8aa3b, v95
	v_mul_f32_e32 v84, 0xbfb8aa3b, v84
	v_mul_f32_e32 v85, 0xbfb8aa3b, v85
	v_mul_f32_e32 v86, 0xbfb8aa3b, v86
	v_mul_f32_e32 v87, 0xbfb8aa3b, v87
	v_mul_f32_e32 v80, 0xbfb8aa3b, v80
	v_mul_f32_e32 v81, 0xbfb8aa3b, v81
	v_mul_f32_e32 v82, 0xbfb8aa3b, v82
	v_mul_f32_e32 v83, 0xbfb8aa3b, v83
	v_exp_f32_e32 v104, v104
	v_exp_f32_e32 v105, v105
	v_exp_f32_e32 v106, v106
	v_exp_f32_e32 v107, v107
	v_exp_f32_e32 v92, v92
	v_exp_f32_e32 v93, v93
	v_exp_f32_e32 v94, v94
	v_exp_f32_e32 v95, v95
	v_exp_f32_e32 v84, v84
	v_exp_f32_e32 v85, v85
	v_exp_f32_e32 v86, v86
	v_exp_f32_e32 v87, v87
	v_exp_f32_e32 v80, v80
	v_exp_f32_e32 v81, v81
	v_exp_f32_e32 v82, v82
	v_exp_f32_e32 v83, v83
	v_add_f32_e32 v104, 1.0, v104
	v_add_f32_e32 v105, 1.0, v105
	v_add_f32_e32 v106, 1.0, v106
	v_add_f32_e32 v107, 1.0, v107
	v_add_f32_e32 v92, 1.0, v92
	v_add_f32_e32 v93, 1.0, v93
	v_add_f32_e32 v94, 1.0, v94
	v_add_f32_e32 v95, 1.0, v95
	v_add_f32_e32 v84, 1.0, v84
	v_add_f32_e32 v85, 1.0, v85
	v_add_f32_e32 v86, 1.0, v86
	v_add_f32_e32 v87, 1.0, v87
	v_add_f32_e32 v80, 1.0, v80
	v_add_f32_e32 v81, 1.0, v81
	v_add_f32_e32 v82, 1.0, v82
	v_add_f32_e32 v83, 1.0, v83
	v_rcp_f32_e32 v240, v104
	v_rcp_f32_e32 v241, v105
	v_rcp_f32_e32 v242, v106
	v_rcp_f32_e32 v243, v107
	v_rcp_f32_e32 v244, v92
	v_rcp_f32_e32 v245, v93
	v_rcp_f32_e32 v246, v94
	v_rcp_f32_e32 v247, v95
	v_rcp_f32_e32 v248, v84
	v_rcp_f32_e32 v249, v85
	v_rcp_f32_e32 v250, v86
	v_rcp_f32_e32 v251, v87
	v_rcp_f32_e32 v252, v80
	v_rcp_f32_e32 v253, v81
	v_rcp_f32_e32 v254, v82
	v_rcp_f32_e32 v255, v83
	s_waitcnt vmcnt(24)
	v_lshlrev_b32_e32 v224, 16, v208
	v_and_b32_e32 v225, 0xffff0000, v208
	v_lshlrev_b32_e32 v226, 16, v209
	v_and_b32_e32 v227, 0xffff0000, v209
	v_lshlrev_b32_e32 v228, 16, v216
	v_and_b32_e32 v229, 0xffff0000, v216
	v_lshlrev_b32_e32 v230, 16, v217
	v_and_b32_e32 v231, 0xffff0000, v217
	v_pk_fma_f32 v[104:105], v[240:241], v[224:225], v[228:229]
	v_pk_fma_f32 v[106:107], v[242:243], v[226:227], v[230:231]
	v_lshlrev_b32_e32 v232, 16, v210
	v_and_b32_e32 v233, 0xffff0000, v210
	v_lshlrev_b32_e32 v234, 16, v211
	v_and_b32_e32 v235, 0xffff0000, v211
	v_lshlrev_b32_e32 v236, 16, v218
	v_and_b32_e32 v237, 0xffff0000, v218
	v_lshlrev_b32_e32 v238, 16, v219
	v_and_b32_e32 v239, 0xffff0000, v219
	v_pk_fma_f32 v[92:93], v[244:245], v[232:233], v[236:237]
	v_pk_fma_f32 v[94:95], v[246:247], v[234:235], v[238:239]
	v_lshlrev_b32_e32 v224, 16, v212
	v_and_b32_e32 v225, 0xffff0000, v212
	v_lshlrev_b32_e32 v226, 16, v213
	v_and_b32_e32 v227, 0xffff0000, v213
	v_lshlrev_b32_e32 v228, 16, v220
	v_and_b32_e32 v229, 0xffff0000, v220
	v_lshlrev_b32_e32 v230, 16, v221
	v_and_b32_e32 v231, 0xffff0000, v221
	v_pk_fma_f32 v[84:85], v[248:249], v[224:225], v[228:229]
	v_pk_fma_f32 v[86:87], v[250:251], v[226:227], v[230:231]
	v_lshlrev_b32_e32 v232, 16, v214
	v_and_b32_e32 v233, 0xffff0000, v214
	v_lshlrev_b32_e32 v234, 16, v215
	v_and_b32_e32 v235, 0xffff0000, v215
	v_lshlrev_b32_e32 v236, 16, v222
	v_and_b32_e32 v237, 0xffff0000, v222
	v_lshlrev_b32_e32 v238, 16, v223
	v_and_b32_e32 v239, 0xffff0000, v223
	v_pk_fma_f32 v[80:81], v[252:253], v[232:233], v[236:237]
	v_pk_fma_f32 v[82:83], v[254:255], v[234:235], v[238:239]
	global_load_dwordx2 v[208:209], v[134:135], off nt
	global_load_dwordx2 v[210:211], v[134:135], off offset:32 nt
	global_load_dwordx2 v[212:213], v[134:135], off offset:256 nt
	global_load_dwordx2 v[214:215], v[134:135], off offset:288 nt
	global_load_dwordx2 v[216:217], v[138:139], off
	global_load_dwordx2 v[218:219], v[138:139], off offset:32
	global_load_dwordx2 v[220:221], v[138:139], off offset:256
	global_load_dwordx2 v[222:223], v[138:139], off offset:288
	v_mul_f32_e32 v60, 0xbfb8aa3b, v60
	v_mul_f32_e32 v61, 0xbfb8aa3b, v61
	v_mul_f32_e32 v62, 0xbfb8aa3b, v62
	v_mul_f32_e32 v63, 0xbfb8aa3b, v63
	v_mul_f32_e32 v56, 0xbfb8aa3b, v56
	v_mul_f32_e32 v57, 0xbfb8aa3b, v57
	v_mul_f32_e32 v58, 0xbfb8aa3b, v58
	v_mul_f32_e32 v59, 0xbfb8aa3b, v59
	v_mul_f32_e32 v52, 0xbfb8aa3b, v52
	v_mul_f32_e32 v53, 0xbfb8aa3b, v53
	v_mul_f32_e32 v54, 0xbfb8aa3b, v54
	v_mul_f32_e32 v55, 0xbfb8aa3b, v55
	v_mul_f32_e32 v48, 0xbfb8aa3b, v48
	v_mul_f32_e32 v49, 0xbfb8aa3b, v49
	v_mul_f32_e32 v50, 0xbfb8aa3b, v50
	v_mul_f32_e32 v51, 0xbfb8aa3b, v51
	v_exp_f32_e32 v60, v60
	v_exp_f32_e32 v61, v61
	v_exp_f32_e32 v62, v62
	v_exp_f32_e32 v63, v63
	v_exp_f32_e32 v56, v56
	v_exp_f32_e32 v57, v57
	v_exp_f32_e32 v58, v58
	v_exp_f32_e32 v59, v59
	v_exp_f32_e32 v52, v52
	v_exp_f32_e32 v53, v53
	v_exp_f32_e32 v54, v54
	v_exp_f32_e32 v55, v55
	v_exp_f32_e32 v48, v48
	v_exp_f32_e32 v49, v49
	v_exp_f32_e32 v50, v50
	v_exp_f32_e32 v51, v51
	v_add_f32_e32 v60, 1.0, v60
	v_add_f32_e32 v61, 1.0, v61
	v_add_f32_e32 v62, 1.0, v62
	v_add_f32_e32 v63, 1.0, v63
	v_add_f32_e32 v56, 1.0, v56
	v_add_f32_e32 v57, 1.0, v57
	v_add_f32_e32 v58, 1.0, v58
	v_add_f32_e32 v59, 1.0, v59
	v_add_f32_e32 v52, 1.0, v52
	v_add_f32_e32 v53, 1.0, v53
	v_add_f32_e32 v54, 1.0, v54
	v_add_f32_e32 v55, 1.0, v55
	v_add_f32_e32 v48, 1.0, v48
	v_add_f32_e32 v49, 1.0, v49
	v_add_f32_e32 v50, 1.0, v50
	v_add_f32_e32 v51, 1.0, v51
	v_rcp_f32_e32 v240, v60
	v_rcp_f32_e32 v241, v61
	v_rcp_f32_e32 v242, v62
	v_rcp_f32_e32 v243, v63
	v_rcp_f32_e32 v244, v56
	v_rcp_f32_e32 v245, v57
	v_rcp_f32_e32 v246, v58
	v_rcp_f32_e32 v247, v59
	v_rcp_f32_e32 v248, v52
	v_rcp_f32_e32 v249, v53
	v_rcp_f32_e32 v250, v54
	v_rcp_f32_e32 v251, v55
	v_rcp_f32_e32 v252, v48
	v_rcp_f32_e32 v253, v49
	v_rcp_f32_e32 v254, v50
	v_rcp_f32_e32 v255, v51
	s_waitcnt vmcnt(24)
	v_lshlrev_b32_e32 v224, 16, v160
	v_and_b32_e32 v225, 0xffff0000, v160
	v_lshlrev_b32_e32 v226, 16, v161
	v_and_b32_e32 v227, 0xffff0000, v161
	v_lshlrev_b32_e32 v228, 16, v168
	v_and_b32_e32 v229, 0xffff0000, v168
	v_lshlrev_b32_e32 v230, 16, v169
	v_and_b32_e32 v231, 0xffff0000, v169
	v_pk_fma_f32 v[60:61], v[240:241], v[224:225], v[228:229]
	v_pk_fma_f32 v[62:63], v[242:243], v[226:227], v[230:231]
	v_lshlrev_b32_e32 v232, 16, v162
	v_and_b32_e32 v233, 0xffff0000, v162
	v_lshlrev_b32_e32 v234, 16, v163
	v_and_b32_e32 v235, 0xffff0000, v163
	v_lshlrev_b32_e32 v236, 16, v170
	v_and_b32_e32 v237, 0xffff0000, v170
	v_lshlrev_b32_e32 v238, 16, v171
	v_and_b32_e32 v239, 0xffff0000, v171
	v_pk_fma_f32 v[56:57], v[244:245], v[232:233], v[236:237]
	v_pk_fma_f32 v[58:59], v[246:247], v[234:235], v[238:239]
	v_lshlrev_b32_e32 v224, 16, v164
	v_and_b32_e32 v225, 0xffff0000, v164
	v_lshlrev_b32_e32 v226, 16, v165
	v_and_b32_e32 v227, 0xffff0000, v165
	v_lshlrev_b32_e32 v228, 16, v172
	v_and_b32_e32 v229, 0xffff0000, v172
	v_lshlrev_b32_e32 v230, 16, v173
	v_and_b32_e32 v231, 0xffff0000, v173
	v_pk_fma_f32 v[52:53], v[248:249], v[224:225], v[228:229]
	v_pk_fma_f32 v[54:55], v[250:251], v[226:227], v[230:231]
	v_lshlrev_b32_e32 v232, 16, v166
	v_and_b32_e32 v233, 0xffff0000, v166
	v_lshlrev_b32_e32 v234, 16, v167
	v_and_b32_e32 v235, 0xffff0000, v167
	v_lshlrev_b32_e32 v236, 16, v174
	v_and_b32_e32 v237, 0xffff0000, v174
	v_lshlrev_b32_e32 v238, 16, v175
	v_and_b32_e32 v239, 0xffff0000, v175
	v_pk_fma_f32 v[48:49], v[252:253], v[232:233], v[236:237]
	v_pk_fma_f32 v[50:51], v[254:255], v[234:235], v[238:239]
	v_mul_f32_e32 v44, 0xbfb8aa3b, v44
	v_mul_f32_e32 v45, 0xbfb8aa3b, v45
	v_mul_f32_e32 v46, 0xbfb8aa3b, v46
	v_mul_f32_e32 v47, 0xbfb8aa3b, v47
	v_mul_f32_e32 v40, 0xbfb8aa3b, v40
	v_mul_f32_e32 v41, 0xbfb8aa3b, v41
	v_mul_f32_e32 v42, 0xbfb8aa3b, v42
	v_mul_f32_e32 v43, 0xbfb8aa3b, v43
	v_mul_f32_e32 v36, 0xbfb8aa3b, v36
	v_mul_f32_e32 v37, 0xbfb8aa3b, v37
	v_mul_f32_e32 v38, 0xbfb8aa3b, v38
	v_mul_f32_e32 v39, 0xbfb8aa3b, v39
	v_mul_f32_e32 v32, 0xbfb8aa3b, v32
	v_mul_f32_e32 v33, 0xbfb8aa3b, v33
	v_mul_f32_e32 v34, 0xbfb8aa3b, v34
	v_mul_f32_e32 v35, 0xbfb8aa3b, v35
	v_exp_f32_e32 v44, v44
	v_exp_f32_e32 v45, v45
	v_exp_f32_e32 v46, v46
	v_exp_f32_e32 v47, v47
	v_exp_f32_e32 v40, v40
	v_exp_f32_e32 v41, v41
	v_exp_f32_e32 v42, v42
	v_exp_f32_e32 v43, v43
	v_exp_f32_e32 v36, v36
	v_exp_f32_e32 v37, v37
	v_exp_f32_e32 v38, v38
	v_exp_f32_e32 v39, v39
	v_exp_f32_e32 v32, v32
	v_exp_f32_e32 v33, v33
	v_exp_f32_e32 v34, v34
	v_exp_f32_e32 v35, v35
	v_add_f32_e32 v44, 1.0, v44
	v_add_f32_e32 v45, 1.0, v45
	v_add_f32_e32 v46, 1.0, v46
	v_add_f32_e32 v47, 1.0, v47
	v_add_f32_e32 v40, 1.0, v40
	v_add_f32_e32 v41, 1.0, v41
	v_add_f32_e32 v42, 1.0, v42
	v_add_f32_e32 v43, 1.0, v43
	v_add_f32_e32 v36, 1.0, v36
	v_add_f32_e32 v37, 1.0, v37
	v_add_f32_e32 v38, 1.0, v38
	v_add_f32_e32 v39, 1.0, v39
	v_add_f32_e32 v32, 1.0, v32
	v_add_f32_e32 v33, 1.0, v33
	v_add_f32_e32 v34, 1.0, v34
	v_add_f32_e32 v35, 1.0, v35
	v_rcp_f32_e32 v240, v44
	v_rcp_f32_e32 v241, v45
	v_rcp_f32_e32 v242, v46
	v_rcp_f32_e32 v243, v47
	v_rcp_f32_e32 v244, v40
	v_rcp_f32_e32 v245, v41
	v_rcp_f32_e32 v246, v42
	v_rcp_f32_e32 v247, v43
	v_rcp_f32_e32 v248, v36
	v_rcp_f32_e32 v249, v37
	v_rcp_f32_e32 v250, v38
	v_rcp_f32_e32 v251, v39
	v_rcp_f32_e32 v252, v32
	v_rcp_f32_e32 v253, v33
	v_rcp_f32_e32 v254, v34
	v_rcp_f32_e32 v255, v35
	s_waitcnt vmcnt(16)
	v_lshlrev_b32_e32 v224, 16, v176
	v_and_b32_e32 v225, 0xffff0000, v176
	v_lshlrev_b32_e32 v226, 16, v177
	v_and_b32_e32 v227, 0xffff0000, v177
	v_lshlrev_b32_e32 v228, 16, v184
	v_and_b32_e32 v229, 0xffff0000, v184
	v_lshlrev_b32_e32 v230, 16, v185
	v_and_b32_e32 v231, 0xffff0000, v185
	v_pk_fma_f32 v[44:45], v[240:241], v[224:225], v[228:229]
	v_pk_fma_f32 v[46:47], v[242:243], v[226:227], v[230:231]
	v_lshlrev_b32_e32 v232, 16, v178
	v_and_b32_e32 v233, 0xffff0000, v178
	v_lshlrev_b32_e32 v234, 16, v179
	v_and_b32_e32 v235, 0xffff0000, v179
	v_lshlrev_b32_e32 v236, 16, v186
	v_and_b32_e32 v237, 0xffff0000, v186
	v_lshlrev_b32_e32 v238, 16, v187
	v_and_b32_e32 v239, 0xffff0000, v187
	v_pk_fma_f32 v[40:41], v[244:245], v[232:233], v[236:237]
	v_pk_fma_f32 v[42:43], v[246:247], v[234:235], v[238:239]
	v_lshlrev_b32_e32 v224, 16, v180
	v_and_b32_e32 v225, 0xffff0000, v180
	v_lshlrev_b32_e32 v226, 16, v181
	v_and_b32_e32 v227, 0xffff0000, v181
	v_lshlrev_b32_e32 v228, 16, v188
	v_and_b32_e32 v229, 0xffff0000, v188
	v_lshlrev_b32_e32 v230, 16, v189
	v_and_b32_e32 v231, 0xffff0000, v189
	v_pk_fma_f32 v[36:37], v[248:249], v[224:225], v[228:229]
	v_pk_fma_f32 v[38:39], v[250:251], v[226:227], v[230:231]
	v_lshlrev_b32_e32 v232, 16, v182
	v_and_b32_e32 v233, 0xffff0000, v182
	v_lshlrev_b32_e32 v234, 16, v183
	v_and_b32_e32 v235, 0xffff0000, v183
	v_lshlrev_b32_e32 v236, 16, v190
	v_and_b32_e32 v237, 0xffff0000, v190
	v_lshlrev_b32_e32 v238, 16, v191
	v_and_b32_e32 v239, 0xffff0000, v191
	v_pk_fma_f32 v[32:33], v[252:253], v[232:233], v[236:237]
	v_pk_fma_f32 v[34:35], v[254:255], v[234:235], v[238:239]
	v_mul_f32_e32 v28, 0xbfb8aa3b, v28
	v_mul_f32_e32 v29, 0xbfb8aa3b, v29
	v_mul_f32_e32 v30, 0xbfb8aa3b, v30
	v_mul_f32_e32 v31, 0xbfb8aa3b, v31
	v_mul_f32_e32 v24, 0xbfb8aa3b, v24
	v_mul_f32_e32 v25, 0xbfb8aa3b, v25
	v_mul_f32_e32 v26, 0xbfb8aa3b, v26
	v_mul_f32_e32 v27, 0xbfb8aa3b, v27
	v_mul_f32_e32 v20, 0xbfb8aa3b, v20
	v_mul_f32_e32 v21, 0xbfb8aa3b, v21
	v_mul_f32_e32 v22, 0xbfb8aa3b, v22
	v_mul_f32_e32 v23, 0xbfb8aa3b, v23
	v_mul_f32_e32 v16, 0xbfb8aa3b, v16
	v_mul_f32_e32 v17, 0xbfb8aa3b, v17
	v_mul_f32_e32 v18, 0xbfb8aa3b, v18
	v_mul_f32_e32 v19, 0xbfb8aa3b, v19
	v_exp_f32_e32 v28, v28
	v_exp_f32_e32 v29, v29
	v_exp_f32_e32 v30, v30
	v_exp_f32_e32 v31, v31
	v_exp_f32_e32 v24, v24
	v_exp_f32_e32 v25, v25
	v_exp_f32_e32 v26, v26
	v_exp_f32_e32 v27, v27
	v_exp_f32_e32 v20, v20
	v_exp_f32_e32 v21, v21
	v_exp_f32_e32 v22, v22
	v_exp_f32_e32 v23, v23
	v_exp_f32_e32 v16, v16
	v_exp_f32_e32 v17, v17
	v_exp_f32_e32 v18, v18
	v_exp_f32_e32 v19, v19
	v_add_f32_e32 v28, 1.0, v28
	v_add_f32_e32 v29, 1.0, v29
	v_add_f32_e32 v30, 1.0, v30
	v_add_f32_e32 v31, 1.0, v31
	v_add_f32_e32 v24, 1.0, v24
	v_add_f32_e32 v25, 1.0, v25
	v_add_f32_e32 v26, 1.0, v26
	v_add_f32_e32 v27, 1.0, v27
	v_add_f32_e32 v20, 1.0, v20
	v_add_f32_e32 v21, 1.0, v21
	v_add_f32_e32 v22, 1.0, v22
	v_add_f32_e32 v23, 1.0, v23
	v_add_f32_e32 v16, 1.0, v16
	v_add_f32_e32 v17, 1.0, v17
	v_add_f32_e32 v18, 1.0, v18
	v_add_f32_e32 v19, 1.0, v19
	v_rcp_f32_e32 v240, v28
	v_rcp_f32_e32 v241, v29
	v_rcp_f32_e32 v242, v30
	v_rcp_f32_e32 v243, v31
	v_rcp_f32_e32 v244, v24
	v_rcp_f32_e32 v245, v25
	v_rcp_f32_e32 v246, v26
	v_rcp_f32_e32 v247, v27
	v_rcp_f32_e32 v248, v20
	v_rcp_f32_e32 v249, v21
	v_rcp_f32_e32 v250, v22
	v_rcp_f32_e32 v251, v23
	v_rcp_f32_e32 v252, v16
	v_rcp_f32_e32 v253, v17
	v_rcp_f32_e32 v254, v18
	v_rcp_f32_e32 v255, v19
	s_waitcnt vmcnt(8)
	v_lshlrev_b32_e32 v224, 16, v192
	v_and_b32_e32 v225, 0xffff0000, v192
	v_lshlrev_b32_e32 v226, 16, v193
	v_and_b32_e32 v227, 0xffff0000, v193
	v_lshlrev_b32_e32 v228, 16, v200
	v_and_b32_e32 v229, 0xffff0000, v200
	v_lshlrev_b32_e32 v230, 16, v201
	v_and_b32_e32 v231, 0xffff0000, v201
	v_pk_fma_f32 v[28:29], v[240:241], v[224:225], v[228:229]
	v_pk_fma_f32 v[30:31], v[242:243], v[226:227], v[230:231]
	v_lshlrev_b32_e32 v232, 16, v194
	v_and_b32_e32 v233, 0xffff0000, v194
	v_lshlrev_b32_e32 v234, 16, v195
	v_and_b32_e32 v235, 0xffff0000, v195
	v_lshlrev_b32_e32 v236, 16, v202
	v_and_b32_e32 v237, 0xffff0000, v202
	v_lshlrev_b32_e32 v238, 16, v203
	v_and_b32_e32 v239, 0xffff0000, v203
	v_pk_fma_f32 v[24:25], v[244:245], v[232:233], v[236:237]
	v_pk_fma_f32 v[26:27], v[246:247], v[234:235], v[238:239]
	v_lshlrev_b32_e32 v224, 16, v196
	v_and_b32_e32 v225, 0xffff0000, v196
	v_lshlrev_b32_e32 v226, 16, v197
	v_and_b32_e32 v227, 0xffff0000, v197
	v_lshlrev_b32_e32 v228, 16, v204
	v_and_b32_e32 v229, 0xffff0000, v204
	v_lshlrev_b32_e32 v230, 16, v205
	v_and_b32_e32 v231, 0xffff0000, v205
	v_pk_fma_f32 v[20:21], v[248:249], v[224:225], v[228:229]
	v_pk_fma_f32 v[22:23], v[250:251], v[226:227], v[230:231]
	v_lshlrev_b32_e32 v232, 16, v198
	v_and_b32_e32 v233, 0xffff0000, v198
	v_lshlrev_b32_e32 v234, 16, v199
	v_and_b32_e32 v235, 0xffff0000, v199
	v_lshlrev_b32_e32 v236, 16, v206
	v_and_b32_e32 v237, 0xffff0000, v206
	v_lshlrev_b32_e32 v238, 16, v207
	v_and_b32_e32 v239, 0xffff0000, v207
	v_pk_fma_f32 v[16:17], v[252:253], v[232:233], v[236:237]
	v_pk_fma_f32 v[18:19], v[254:255], v[234:235], v[238:239]
	v_mul_f32_e32 v12, 0xbfb8aa3b, v12
	v_mul_f32_e32 v13, 0xbfb8aa3b, v13
	v_mul_f32_e32 v14, 0xbfb8aa3b, v14
	v_mul_f32_e32 v15, 0xbfb8aa3b, v15
	v_mul_f32_e32 v8, 0xbfb8aa3b, v8
	v_mul_f32_e32 v9, 0xbfb8aa3b, v9
	v_mul_f32_e32 v10, 0xbfb8aa3b, v10
	v_mul_f32_e32 v11, 0xbfb8aa3b, v11
	v_mul_f32_e32 v4, 0xbfb8aa3b, v4
	v_mul_f32_e32 v5, 0xbfb8aa3b, v5
	v_mul_f32_e32 v6, 0xbfb8aa3b, v6
	v_mul_f32_e32 v7, 0xbfb8aa3b, v7
	v_mul_f32_e32 v0, 0xbfb8aa3b, v0
	v_mul_f32_e32 v1, 0xbfb8aa3b, v1
	v_mul_f32_e32 v2, 0xbfb8aa3b, v2
	v_mul_f32_e32 v3, 0xbfb8aa3b, v3
	v_exp_f32_e32 v12, v12
	v_exp_f32_e32 v13, v13
	v_exp_f32_e32 v14, v14
	v_exp_f32_e32 v15, v15
	v_exp_f32_e32 v8, v8
	v_exp_f32_e32 v9, v9
	v_exp_f32_e32 v10, v10
	v_exp_f32_e32 v11, v11
	v_exp_f32_e32 v4, v4
	v_exp_f32_e32 v5, v5
	v_exp_f32_e32 v6, v6
	v_exp_f32_e32 v7, v7
	v_exp_f32_e32 v0, v0
	v_exp_f32_e32 v1, v1
	v_exp_f32_e32 v2, v2
	v_exp_f32_e32 v3, v3
	v_add_f32_e32 v12, 1.0, v12
	v_add_f32_e32 v13, 1.0, v13
	v_add_f32_e32 v14, 1.0, v14
	v_add_f32_e32 v15, 1.0, v15
	v_add_f32_e32 v8, 1.0, v8
	v_add_f32_e32 v9, 1.0, v9
	v_add_f32_e32 v10, 1.0, v10
	v_add_f32_e32 v11, 1.0, v11
	v_add_f32_e32 v4, 1.0, v4
	v_add_f32_e32 v5, 1.0, v5
	v_add_f32_e32 v6, 1.0, v6
	v_add_f32_e32 v7, 1.0, v7
	v_add_f32_e32 v0, 1.0, v0
	v_add_f32_e32 v1, 1.0, v1
	v_add_f32_e32 v2, 1.0, v2
	v_add_f32_e32 v3, 1.0, v3
	v_rcp_f32_e32 v240, v12
	v_rcp_f32_e32 v241, v13
	v_rcp_f32_e32 v242, v14
	v_rcp_f32_e32 v243, v15
	v_rcp_f32_e32 v244, v8
	v_rcp_f32_e32 v245, v9
	v_rcp_f32_e32 v246, v10
	v_rcp_f32_e32 v247, v11
	v_rcp_f32_e32 v248, v4
	v_rcp_f32_e32 v249, v5
	v_rcp_f32_e32 v250, v6
	v_rcp_f32_e32 v251, v7
	v_rcp_f32_e32 v252, v0
	v_rcp_f32_e32 v253, v1
	v_rcp_f32_e32 v254, v2
	v_rcp_f32_e32 v255, v3
	s_waitcnt vmcnt(0)
	v_lshlrev_b32_e32 v224, 16, v208
	v_and_b32_e32 v225, 0xffff0000, v208
	v_lshlrev_b32_e32 v226, 16, v209
	v_and_b32_e32 v227, 0xffff0000, v209
	v_lshlrev_b32_e32 v228, 16, v216
	v_and_b32_e32 v229, 0xffff0000, v216
	v_lshlrev_b32_e32 v230, 16, v217
	v_and_b32_e32 v231, 0xffff0000, v217
	v_pk_fma_f32 v[12:13], v[240:241], v[224:225], v[228:229]
	v_pk_fma_f32 v[14:15], v[242:243], v[226:227], v[230:231]
	v_lshlrev_b32_e32 v232, 16, v210
	v_and_b32_e32 v233, 0xffff0000, v210
	v_lshlrev_b32_e32 v234, 16, v211
	v_and_b32_e32 v235, 0xffff0000, v211
	v_lshlrev_b32_e32 v236, 16, v218
	v_and_b32_e32 v237, 0xffff0000, v218
	v_lshlrev_b32_e32 v238, 16, v219
	v_and_b32_e32 v239, 0xffff0000, v219
	v_pk_fma_f32 v[8:9], v[244:245], v[232:233], v[236:237]
	v_pk_fma_f32 v[10:11], v[246:247], v[234:235], v[238:239]
	v_lshlrev_b32_e32 v224, 16, v212
	v_and_b32_e32 v225, 0xffff0000, v212
	v_lshlrev_b32_e32 v226, 16, v213
	v_and_b32_e32 v227, 0xffff0000, v213
	v_lshlrev_b32_e32 v228, 16, v220
	v_and_b32_e32 v229, 0xffff0000, v220
	v_lshlrev_b32_e32 v230, 16, v221
	v_and_b32_e32 v231, 0xffff0000, v221
	v_pk_fma_f32 v[4:5], v[248:249], v[224:225], v[228:229]
	v_pk_fma_f32 v[6:7], v[250:251], v[226:227], v[230:231]
	v_lshlrev_b32_e32 v232, 16, v214
	v_and_b32_e32 v233, 0xffff0000, v214
	v_lshlrev_b32_e32 v234, 16, v215
	v_and_b32_e32 v235, 0xffff0000, v215
	v_lshlrev_b32_e32 v236, 16, v222
	v_and_b32_e32 v237, 0xffff0000, v222
	v_lshlrev_b32_e32 v238, 16, v223
	v_and_b32_e32 v239, 0xffff0000, v223
	v_pk_fma_f32 v[0:1], v[252:253], v[232:233], v[236:237]
	v_pk_fma_f32 v[2:3], v[254:255], v[234:235], v[238:239]
	v_mul_f32_e32 v133, v71, v71
	v_fmac_f32_e32 v133, v70, v70
	v_and_b32_e32 v132, 63, v142
	s_lshl_b32 s4, s19, 2
	v_cmp_gt_u32_e32 vcc, 16, v132
	s_add_i32 s16, s4, 0
	v_mul_f32_e32 v130, v65, v65
	v_mul_f32_e32 v131, v67, v67
	v_fmac_f32_e32 v130, v64, v64
	v_fmac_f32_e32 v131, v66, v66
	v_add_f32_e32 v130, v130, v131
	v_mul_f32_e32 v131, v69, v69
	v_fmac_f32_e32 v131, v68, v68
	v_add_f32_e32 v131, v131, v133
	v_add_f32_e32 v130, v130, v131
	v_mul_f32_e32 v131, v73, v73
	v_mul_f32_e32 v133, v75, v75
	v_fmac_f32_e32 v131, v72, v72
	v_fmac_f32_e32 v133, v74, v74
	v_add_f32_e32 v131, v131, v133
	v_add_f32_e32 v130, v131, v130
	v_mul_f32_e32 v131, v77, v77
	v_mul_f32_e32 v133, v79, v79
	v_fmac_f32_e32 v131, v76, v76
	v_fmac_f32_e32 v133, v78, v78
	v_add_f32_e32 v131, v131, v133
	v_add_f32_e32 v130, v131, v130
	ds_swizzle_b32 v131, v130 offset:swizzle(SWAP,16)
	s_waitcnt lgkmcnt(0)
	v_add_f32_e32 v130, v130, v131
	v_mov_b32_e32 v131, v130
	s_nop 1
	v_permlane32_swap_b32_e32 v130, v131
	s_and_saveexec_b64 s[4:5], vcc
	s_lshl_b32 s17, s54, 10
	s_add_i32 s17, s16, s17
	v_lshl_add_u32 v133, v143, 4, s17
	v_add_f32_e32 v130, v130, v131
	ds_write_b32 v133, v130
	s_or_b64 exec, exec, s[4:5]
	v_mul_f32_e32 v130, v89, v89
	v_mul_f32_e32 v131, v91, v91
	v_fmac_f32_e32 v130, v88, v88
	v_fmac_f32_e32 v131, v90, v90
	v_add_f32_e32 v130, v130, v131
	v_mul_f32_e32 v131, v97, v97
	v_mul_f32_e32 v133, v99, v99
	v_fmac_f32_e32 v131, v96, v96
	v_fmac_f32_e32 v133, v98, v98
	v_add_f32_e32 v131, v131, v133
	v_add_f32_e32 v130, v130, v131
	v_mul_f32_e32 v131, v101, v101
	v_mul_f32_e32 v133, v103, v103
	v_fmac_f32_e32 v131, v100, v100
	v_fmac_f32_e32 v133, v102, v102
	v_add_f32_e32 v131, v131, v133
	v_add_f32_e32 v130, v131, v130
	v_mul_f32_e32 v131, v109, v109
	v_mul_f32_e32 v133, v111, v111
	v_fmac_f32_e32 v131, v108, v108
	v_fmac_f32_e32 v133, v110, v110
	v_add_f32_e32 v131, v131, v133
	v_add_f32_e32 v130, v131, v130
	ds_swizzle_b32 v131, v130 offset:swizzle(SWAP,16)
	s_waitcnt lgkmcnt(0)
	v_add_f32_e32 v130, v130, v131
	v_mov_b32_e32 v131, v130
	s_nop 1
	v_permlane32_swap_b32_e32 v130, v131
	s_and_saveexec_b64 s[4:5], vcc
	s_lshl_b32 s17, s54, 10
	s_add_i32 s17, s16, s17
	v_lshl_add_u32 v133, v143, 4, s17
	v_add_f32_e32 v130, v130, v131
	ds_write_b32 v133, v130 offset:256
	s_or_b64 exec, exec, s[4:5]
	v_mul_f32_e32 v130, v121, v121
	v_mul_f32_e32 v131, v123, v123
	v_fmac_f32_e32 v130, v120, v120
	v_fmac_f32_e32 v131, v122, v122
	v_add_f32_e32 v130, v130, v131
	v_mul_f32_e32 v131, v125, v125
	v_mul_f32_e32 v133, v127, v127
	v_fmac_f32_e32 v131, v124, v124
	v_fmac_f32_e32 v133, v126, v126
	v_add_f32_e32 v131, v131, v133
	v_add_f32_e32 v130, v130, v131
	v_mul_f32_e32 v131, v117, v117
	v_mul_f32_e32 v133, v119, v119
	v_fmac_f32_e32 v131, v116, v116
	v_fmac_f32_e32 v133, v118, v118
	v_add_f32_e32 v131, v131, v133
	v_add_f32_e32 v130, v131, v130
	v_mul_f32_e32 v131, v113, v113
	v_mul_f32_e32 v133, v115, v115
	v_fmac_f32_e32 v131, v112, v112
	v_fmac_f32_e32 v133, v114, v114
	v_add_f32_e32 v131, v131, v133
	v_add_f32_e32 v130, v131, v130
	ds_swizzle_b32 v131, v130 offset:swizzle(SWAP,16)
	s_waitcnt lgkmcnt(0)
	v_add_f32_e32 v130, v130, v131
	v_mov_b32_e32 v131, v130
	s_nop 1
	v_permlane32_swap_b32_e32 v130, v131
	s_and_saveexec_b64 s[4:5], vcc
	s_lshl_b32 s17, s54, 10
	s_add_i32 s17, s16, s17
	v_lshl_add_u32 v133, v143, 4, s17
	v_add_f32_e32 v130, v130, v131
	ds_write_b32 v133, v130 offset:512
	s_or_b64 exec, exec, s[4:5]
	v_mul_f32_e32 v130, v105, v105
	v_mul_f32_e32 v131, v107, v107
	v_fmac_f32_e32 v130, v104, v104
	v_fmac_f32_e32 v131, v106, v106
	v_add_f32_e32 v130, v130, v131
	v_mul_f32_e32 v131, v93, v93
	v_mul_f32_e32 v133, v95, v95
	v_fmac_f32_e32 v131, v92, v92
	v_fmac_f32_e32 v133, v94, v94
	v_add_f32_e32 v131, v131, v133
	v_add_f32_e32 v130, v130, v131
	v_mul_f32_e32 v131, v85, v85
	v_mul_f32_e32 v133, v87, v87
	v_fmac_f32_e32 v131, v84, v84
	v_fmac_f32_e32 v133, v86, v86
	v_add_f32_e32 v131, v131, v133
	v_add_f32_e32 v130, v131, v130
	v_mul_f32_e32 v131, v81, v81
	v_mul_f32_e32 v133, v83, v83
	v_fmac_f32_e32 v131, v80, v80
	v_fmac_f32_e32 v133, v82, v82
	v_add_f32_e32 v131, v131, v133
	v_add_f32_e32 v130, v131, v130
	ds_swizzle_b32 v131, v130 offset:swizzle(SWAP,16)
	s_waitcnt lgkmcnt(0)
	v_add_f32_e32 v130, v130, v131
	v_mov_b32_e32 v131, v130
	s_nop 1
	v_permlane32_swap_b32_e32 v130, v131
	s_and_saveexec_b64 s[4:5], vcc
	s_lshl_b32 s17, s54, 10
	s_add_i32 s17, s16, s17
	v_lshl_add_u32 v133, v143, 4, s17
	v_add_f32_e32 v130, v130, v131
	ds_write_b32 v133, v130 offset:768
	s_or_b64 exec, exec, s[4:5]
	v_mul_f32_e32 v130, v61, v61
	v_mul_f32_e32 v131, v63, v63
	v_fmac_f32_e32 v130, v60, v60
	v_fmac_f32_e32 v131, v62, v62
	v_add_f32_e32 v130, v130, v131
	v_mul_f32_e32 v131, v57, v57
	v_mul_f32_e32 v133, v59, v59
	v_fmac_f32_e32 v131, v56, v56
	v_fmac_f32_e32 v133, v58, v58
	v_add_f32_e32 v131, v131, v133
	v_add_f32_e32 v130, v130, v131
	v_mul_f32_e32 v131, v53, v53
	v_mul_f32_e32 v133, v55, v55
	v_fmac_f32_e32 v131, v52, v52
	v_fmac_f32_e32 v133, v54, v54
	v_add_f32_e32 v131, v131, v133
	v_add_f32_e32 v130, v131, v130
	v_mul_f32_e32 v131, v49, v49
	v_mul_f32_e32 v133, v51, v51
	v_fmac_f32_e32 v131, v48, v48
	v_fmac_f32_e32 v133, v50, v50
	v_add_f32_e32 v131, v131, v133
	v_add_f32_e32 v130, v131, v130
	ds_swizzle_b32 v131, v130 offset:swizzle(SWAP,16)
	s_waitcnt lgkmcnt(0)
	v_add_f32_e32 v130, v130, v131
	v_mov_b32_e32 v131, v130
	s_nop 1
	v_permlane32_swap_b32_e32 v130, v131
	s_and_saveexec_b64 s[4:5], vcc
	s_lshl_b32 s17, s54, 10
	s_add_i32 s17, s16, s17
	v_lshl_add_u32 v133, v143, 4, s17
	v_add_f32_e32 v130, v130, v131
	ds_write_b32 v133, v130 offset:2048
	s_or_b64 exec, exec, s[4:5]
	v_mul_f32_e32 v130, v45, v45
	v_mul_f32_e32 v131, v47, v47
	v_fmac_f32_e32 v130, v44, v44
	v_fmac_f32_e32 v131, v46, v46
	v_add_f32_e32 v130, v130, v131
	v_mul_f32_e32 v131, v41, v41
	v_mul_f32_e32 v133, v43, v43
	v_fmac_f32_e32 v131, v40, v40
	v_fmac_f32_e32 v133, v42, v42
	v_add_f32_e32 v131, v131, v133
	v_add_f32_e32 v130, v130, v131
	v_mul_f32_e32 v131, v37, v37
	v_mul_f32_e32 v133, v39, v39
	v_fmac_f32_e32 v131, v36, v36
	v_fmac_f32_e32 v133, v38, v38
	v_add_f32_e32 v131, v131, v133
	v_add_f32_e32 v130, v131, v130
	v_mul_f32_e32 v131, v33, v33
	v_mul_f32_e32 v133, v35, v35
	v_fmac_f32_e32 v131, v32, v32
	v_fmac_f32_e32 v133, v34, v34
	v_add_f32_e32 v131, v131, v133
	v_add_f32_e32 v130, v131, v130
	ds_swizzle_b32 v131, v130 offset:swizzle(SWAP,16)
	s_waitcnt lgkmcnt(0)
	v_add_f32_e32 v130, v130, v131
	v_mov_b32_e32 v131, v130
	s_nop 1
	v_permlane32_swap_b32_e32 v130, v131
	s_and_saveexec_b64 s[4:5], vcc
	s_lshl_b32 s17, s54, 10
	s_add_i32 s17, s16, s17
	v_lshl_add_u32 v133, v143, 4, s17
	v_add_f32_e32 v130, v130, v131
	ds_write_b32 v133, v130 offset:2304
	s_or_b64 exec, exec, s[4:5]
	v_mul_f32_e32 v130, v29, v29
	v_mul_f32_e32 v131, v31, v31
	v_fmac_f32_e32 v130, v28, v28
	v_fmac_f32_e32 v131, v30, v30
	v_add_f32_e32 v130, v130, v131
	v_mul_f32_e32 v131, v25, v25
	v_mul_f32_e32 v133, v27, v27
	v_fmac_f32_e32 v131, v24, v24
	v_fmac_f32_e32 v133, v26, v26
	v_add_f32_e32 v131, v131, v133
	v_add_f32_e32 v130, v130, v131
	v_mul_f32_e32 v131, v21, v21
	v_mul_f32_e32 v133, v23, v23
	v_fmac_f32_e32 v131, v20, v20
	v_fmac_f32_e32 v133, v22, v22
	v_add_f32_e32 v131, v131, v133
	v_add_f32_e32 v130, v131, v130
	v_mul_f32_e32 v131, v17, v17
	v_mul_f32_e32 v133, v19, v19
	v_fmac_f32_e32 v131, v16, v16
	v_fmac_f32_e32 v133, v18, v18
	v_add_f32_e32 v131, v131, v133
	v_add_f32_e32 v130, v131, v130
	ds_swizzle_b32 v131, v130 offset:swizzle(SWAP,16)
	s_waitcnt lgkmcnt(0)
	v_add_f32_e32 v130, v130, v131
	v_mov_b32_e32 v131, v130
	s_nop 1
	v_permlane32_swap_b32_e32 v130, v131
	s_and_saveexec_b64 s[4:5], vcc
	s_lshl_b32 s17, s54, 10
	s_add_i32 s17, s16, s17
	v_lshl_add_u32 v133, v143, 4, s17
	v_add_f32_e32 v130, v130, v131
	ds_write_b32 v133, v130 offset:2560
	s_or_b64 exec, exec, s[4:5]
	v_mul_f32_e32 v130, v13, v13
	v_mul_f32_e32 v131, v15, v15
	v_fmac_f32_e32 v130, v12, v12
	v_fmac_f32_e32 v131, v14, v14
	v_add_f32_e32 v130, v130, v131
	v_mul_f32_e32 v131, v9, v9
	v_mul_f32_e32 v133, v11, v11
	v_fmac_f32_e32 v131, v8, v8
	v_fmac_f32_e32 v133, v10, v10
	v_add_f32_e32 v131, v131, v133
	v_add_f32_e32 v130, v130, v131
	v_mul_f32_e32 v131, v5, v5
	v_mul_f32_e32 v133, v7, v7
	v_fmac_f32_e32 v131, v4, v4
	v_fmac_f32_e32 v133, v6, v6
	v_add_f32_e32 v131, v131, v133
	v_add_f32_e32 v130, v131, v130
	v_mul_f32_e32 v131, v1, v1
	v_mul_f32_e32 v133, v3, v3
	v_fmac_f32_e32 v131, v0, v0
	v_fmac_f32_e32 v133, v2, v2
	v_add_f32_e32 v131, v131, v133
	v_add_f32_e32 v130, v131, v130
	ds_swizzle_b32 v131, v130 offset:swizzle(SWAP,16)
	s_waitcnt lgkmcnt(0)
	v_add_f32_e32 v130, v130, v131
	v_mov_b32_e32 v131, v130
	s_nop 1
	v_permlane32_swap_b32_e32 v130, v131
	s_and_saveexec_b64 s[4:5], vcc
	s_lshl_b32 s17, s54, 10
	s_add_i32 s16, s16, s17
	v_lshl_add_u32 v133, v143, 4, s16
	v_add_f32_e32 v130, v130, v131
	ds_write_b32 v133, v130 offset:2816
	s_or_b64 exec, exec, s[4:5]
	v_and_b32_e32 v130, 31, v142
	s_waitcnt lgkmcnt(0)
	s_barrier
	v_lshl_or_b32 v133, s49, 5, v130
	s_add_u32 s16, s12, 0xa0000
	v_add_u32_e32 v130, s24, v133
	s_addc_u32 s17, s13, 0
	v_cmp_gt_u32_e64 s[4:5], 32, v132
	v_ashrrev_i32_e32 v131, 31, v130
	s_and_saveexec_b64 s[22:23], s[4:5]
	s_cbranch_execz .LBB0_1152
	v_lshl_add_u32 v134, v133, 4, 0
	ds_read_b128 v[134:137], v134
	s_ashr_i32 s21, s20, 31
	v_lshl_add_u64 v[138:139], v[130:131], 4, s[16:17]
	s_waitcnt lgkmcnt(0)
	v_mov_b32_e32 v140, v135
	v_mov_b32_e32 v141, v136
	v_mov_b32_e32 v135, v137
	v_pk_add_f32 v[134:135], v[140:141], v[134:135]
	v_lshl_add_u64 v[136:137], s[20:21], 2, v[138:139]
	v_pk_add_f32 v[134:135], v[134:135], v[134:135] op_sel:[0,1] op_sel_hi:[1,0]
	global_store_dword v[136:137], v134, off sc1
